# h2 short-conv ctx-token loop: 9 dependent global round trips per element replaced by one batch of 21 loads (SGPR base + 32-bit offsets, boundary rows clamped)
# speedup vs baseline: 1.0081x; 1.0081x over previous
; __device__ __forceinline__ void h2_shortconv(const KQ p_in, int o, int M, unsigned char* smem) {
;     ...
;     __syncthreads();
;     if (M > TL) {
;         float* VX = (float*)(p.ws + WS_Y); bf16_t* X0 = (bf16_t*)(p.ws + WS_H);
;         for (int idx = TL * D + blockIdx.x * 512 + tid; idx < M * D; idx += gridDim.x * 512) {
;             const int t = idx >> 10, d = idx & 1023;
.LBB0_435:
	v_readlane_b32 s0, v252, 36
	v_readlane_b32 s1, v252, 37
	s_and_b64 vcc, exec, s[0:1]
	s_waitcnt lgkmcnt(0)
	s_barrier
	s_cbranch_vccz .LBB0_452
	v_readlane_b32 s0, v251, 35
	s_nop 1
	v_add_u32_e32 v0, s0, v133
	v_readlane_b32 s0, v252, 52
	s_nop 1
	v_cmp_gt_i32_e32 vcc, s0, v0
	s_and_saveexec_b64 s[0:1], vcc
	s_cbranch_execz .LBB0_451
	s_add_u32 s12, s12, 0xa9b4000
	s_addc_u32 s13, s13, 0
	s_mov_b64 s[14:15], 0
	s_add_u32 s98, s4, 0x3000
	s_addc_u32 s99, s5, 0
	s_add_u32 s100, s4, 0x6000
	s_addc_u32 s101, s5, 0
	s_branch .LBB0_439

; __device__ __forceinline__ float bf2f(bf16_t b) { return __uint_as_float(((unsigned)b) << 16); }
; __device__ __forceinline__ void h2_shortconv(const KQ p_in, int o, int M, unsigned char* smem) {
;     ...
;             const int t = idx >> 10, d = idx & 1023;
;             const int pos = (t - TL) & (CL - 1); const bool first = pos == 0, last = pos == CL - 1;
;             float zz[3];
; #pragma unroll
;             for (int k = 0; k < 3; ++k) {
;                 const int c = k * 1024 + d;
;                 float sacc = bs[c] + bf2f(ZH[(size_t)t * HYW + c]) * w[HYW + c];
;                 if (!first) sacc += bf2f(ZH[(size_t)(t - 1) * HYW + c]) * w[c];
;                 if (!last) sacc += bf2f(ZH[(size_t)(t + 1) * HYW + c]) * w[2 * HYW + c];
;                 zz[k] = sacc;
;             }
.LBB0_439:
	v_ashrrev_i32_e32 v6, 10, v0
	v_and_b32_e32 v1, 0x3ff, v0
	v_cmp_ne_u32_sdwa s[16:17], v6, v145 src0_sel:BYTE_0 src1_sel:DWORD
	v_cmp_ne_u32_sdwa s[18:19], v6, s31 src0_sel:BYTE_0 src1_sel:DWORD
	v_mul_u32_u24_e32 v2, 0x1800, v6
	v_lshlrev_b32_e32 v208, 2, v1
	v_lshl_add_u32 v2, v1, 1, v2
	v_add_u32_e32 v209, 0x1000, v208
	v_add_u32_e32 v210, 0x2000, v208
	v_add_u32_e32 v3, 0xffffe800, v2
	v_add_u32_e32 v4, 0x1800, v2
	v_cndmask_b32_e64 v3, v2, v3, s[16:17]
	v_cndmask_b32_e64 v4, v2, v4, s[18:19]
	v_add_u32_e32 v5, 0x1000, v2
	v_add_u32_e32 v7, 0x1000, v3
	v_add_u32_e32 v8, 0x1000, v4
	global_load_dword v12, v208, s[6:7]
	global_load_dword v10, v209, s[6:7]
	global_load_dword v1, v210, s[6:7]
	global_load_ushort v211, v2, s[8:9]
	global_load_ushort v212, v2, s[8:9] offset:2048
	global_load_ushort v213, v5, s[8:9]
	global_load_dword v214, v208, s[98:99]
	global_load_dword v215, v209, s[98:99]
	global_load_dword v216, v210, s[98:99]
	global_load_ushort v217, v3, s[8:9]
	global_load_ushort v218, v3, s[8:9] offset:2048
	global_load_ushort v219, v7, s[8:9]
	global_load_dword v220, v208, s[4:5]
	global_load_dword v221, v209, s[4:5]
	global_load_dword v222, v210, s[4:5]
	global_load_ushort v223, v4, s[8:9]
	global_load_ushort v224, v4, s[8:9] offset:2048
	global_load_ushort v225, v8, s[8:9]
	global_load_dword v226, v208, s[100:101]
	global_load_dword v227, v209, s[100:101]
	global_load_dword v228, v210, s[100:101]
	s_waitcnt vmcnt(12)
	v_lshlrev_b32_e32 v211, 16, v211
	v_lshlrev_b32_e32 v212, 16, v212
	v_lshlrev_b32_e32 v213, 16, v213
	v_fmac_f32_e32 v12, v214, v211
	v_fmac_f32_e32 v10, v215, v212
	v_fmac_f32_e32 v1, v216, v213
	s_waitcnt vmcnt(6)
	s_and_saveexec_b64 s[20:21], s[16:17]
	v_lshlrev_b32_e32 v217, 16, v217
	v_lshlrev_b32_e32 v218, 16, v218
	v_lshlrev_b32_e32 v219, 16, v219
	v_fmac_f32_e32 v12, v220, v217
	v_fmac_f32_e32 v10, v221, v218
	v_fmac_f32_e32 v1, v222, v219
	s_mov_b64 exec, s[20:21]
	s_waitcnt vmcnt(0)
	s_and_saveexec_b64 s[20:21], s[18:19]
	v_lshlrev_b32_e32 v223, 16, v223
	v_lshlrev_b32_e32 v224, 16, v224
	v_lshlrev_b32_e32 v225, 16, v225
	v_fmac_f32_e32 v12, v226, v223
	v_fmac_f32_e32 v10, v227, v224
	v_fmac_f32_e32 v1, v228, v225
	s_mov_b64 exec, s[20:21]
	s_branch .LBB0_438
